# rwkv2 role 1: per-head parameter loads waited once before the chunk loop; beta no longer waits on the next chunk's prefetch loads
# speedup vs baseline: 1.0041x; 1.0009x over previous
; __device__ unsigned long long rwkv2_phase(const Params& p, unsigned char* smem) {
;     ...
;             const int w4 = wave, ptid = tid, k = 16 * w4 + l15, kg = hc + k;
;             const float mu_r = p.in[25][kg], mu_k = p.in[25][4096 + kg], mu_v = p.in[25][8192 + kg];
;             const float w0k = p.in[28][kg], a0k = p.in[31][kg], kkk = p.in[34][kg], kak = p.in[35][kg], rkk = p.in[36][kg];
;             u32x4 pfP[2]; u32x2 pfR[4];
;     ...
;             RW_PREFETCH(0);
.LBB0_947:
	s_andn2_b64 vcc, exec, s[26:27]
	s_cbranch_vccnz .LBB0_844
	v_or_b32_e32 v3, s33, v102
	v_readlane_b32 s16, v251, 16
	v_lshlrev_b32_e32 v4, 2, v3
	v_mov_b32_e32 v5, v2
	v_readlane_b32 s30, v251, 30
	v_readlane_b32 s31, v251, 31
	v_readlane_b32 s17, v251, 17
	v_readlane_b32 s18, v251, 18
	v_lshl_add_u64 v[42:43], s[30:31], 0, v[4:5]
	v_add_co_u32_e32 v44, vcc, 0x4000, v42
	v_readlane_b32 s19, v251, 19
	s_nop 0
	v_addc_co_u32_e32 v45, vcc, 0, v43, vcc
	v_add_co_u32_e32 v42, vcc, 0x8000, v42
	v_readlane_b32 s20, v251, 20
	v_readlane_b32 s21, v251, 21
	v_readlane_b32 s22, v251, 22
	v_readlane_b32 s23, v251, 23
	v_readlane_b32 s24, v251, 24
	v_readlane_b32 s25, v251, 25
	v_readlane_b32 s26, v251, 26
	v_readlane_b32 s27, v251, 27
	v_readlane_b32 s28, v251, 28
	v_readlane_b32 s29, v251, 29
	v_addc_co_u32_e32 v43, vcc, 0, v43, vcc
	global_load_dword v3, v4, s[30:31]
	global_load_dword v60, v[44:45], off
	global_load_dword v61, v[42:43], off
	v_readlane_b32 s16, v251, 47
	v_readlane_b32 s17, v251, 48
	v_readlane_b32 s20, v251, 51
	v_readlane_b32 s21, v251, 52
	v_readlane_b32 s22, v251, 53
	v_readlane_b32 s23, v251, 54
	v_readlane_b32 s24, v251, 55
	v_readlane_b32 s25, v251, 56
	v_readlane_b32 s26, v251, 57
	v_readlane_b32 s27, v251, 58
	s_mov_b64 s[16:17], s[20:21]
	s_mov_b64 s[20:21], s[24:25]
	v_readlane_b32 s18, v251, 49
	v_readlane_b32 s19, v251, 50
	v_readlane_b32 s28, v251, 59
	v_readlane_b32 s29, v251, 60
	v_readlane_b32 s30, v251, 61
	v_readlane_b32 s31, v251, 62
	s_mov_b64 s[22:23], s[26:27]
	global_load_dword v62, v4, s[16:17]
	global_load_dword v63, v4, s[22:23]
	v_readlane_b32 s16, v250, 5
	v_readlane_b32 s17, v250, 6
	v_readlane_b32 s18, v250, 7
	v_readlane_b32 s19, v250, 8
	v_readlane_b32 s20, v250, 9
	v_readlane_b32 s21, v250, 10
	s_nop 0
	global_load_dword v64, v4, s[16:17]
	s_nop 0
	global_load_dword v65, v4, s[18:19]
	s_nop 0
	global_load_dword v66, v4, s[20:21]
	s_waitcnt vmcnt(0)
	v_readlane_b32 s28, v250, 17
	v_readlane_b32 s26, v250, 15
	v_readlane_b32 s27, v250, 16
	s_lshl_b32 s28, s62, 12
	v_readlane_b32 s22, v250, 11
	v_readlane_b32 s23, v250, 12
	v_readlane_b32 s24, v250, 13
	v_readlane_b32 s25, v250, 14
	v_readlane_b32 s29, v250, 18
	v_readlane_b32 s30, v250, 19
	v_readlane_b32 s31, v250, 20
	s_and_saveexec_b64 s[26:27], s[0:1]
	s_cbranch_execz .LBB0_950
	v_or_b32_e32 v4, s28, v144
	v_mad_i64_i32 v[4:5], s[30:31], v4, s95, v[106:107]
	global_load_dwordx4 v[34:37], v[4:5], off

; __device__ unsigned long long rwkv2_phase(const Params& p, unsigned char* smem) {
;     ...
;                 u16* set1 = S1 + (pc & 1) * (4 * 16 * 72);
;                 u16* At = set1; u16* Rt = set1 + 16 * 72; u16* Bt = set1 + 2 * 16 * 72; u16* Kt = set1 + 3 * 16 * 72;
;                 unsigned char* set1b = S1b + (pc % 3) * 10560;
;                 float* Vf = (float*)set1b; u16* BKT = (u16*)(set1b + 4096); u16* VT = (u16*)(set1b + 8192); float* W15 = (float*)(set1b + 10240); float* bonus = (float*)(set1b + 10496);
;                 if (prep) {
; #pragma unroll
;                     for (int i = 0; i < 2; ++i) { const int it = ptid + 256 * i; const int mt = it / 192, rem = it - mt * 192, t_ = rem / 12, g_ = rem - t_ * 12;
;                         if (it < 384) *(u32x4*)(twa + (mt * 16 + t_) * 104 + 8 * g_) = pfP[i]; }
; #pragma unroll
;                     for (int i = 0; i < 4; ++i) { const int it = ptid + 256 * i; const int ar = it / 272, rem = it - ar * 272, rr_ = rem >> 4, c4 = rem & 15;
;                         if (it < 816) *(u32x2*)(raw + (ar * 17 + rr_) * 64 + 4 * c4) = pfR[i]; }
;                 }
;                 if (pc + 1 < NCH) RW_PREFETCH(pc + 1);
;                 LBARW();
;                 float au[4], bu[4];
;                 if (prep) {
;                     float kkv[4], a_[4], eP[4], eTi[4];
;                     f32x4 accW = {0.f, 0.f, 0.f, 0.f}, accA = {0.f, 0.f, 0.f, 0.f};
; #pragma unroll
;                     for (int ks = 0; ks < 3; ++ks) { const bf16x8 afw = *(const bf16x8*)(twa + l15 * 104 + 32 * ks + 8 * lq), afa = *(const bf16x8*)(twa + (16 + l15) * 104 + 32 * ks + 8 * lq);
;                         const bf16x8 bwf = *(const bf16x8*)(W2t + k * 104 + 32 * ks + 8 * lq), baf = *(const bf16x8*)(A2t + k * 104 + 32 * ks + 8 * lq);
;                         accW = MFMA16(afw, bwf, accW); accA = MFMA16(afa, baf, accA); }
;                     float ld[4]; f32x4 cum = {0.f, 0.f, 0.f, 0.f};
; #pragma unroll
;                     for (int r = 0; r < 4; ++r) ld[r] = -0.60653066f * fsigmoid(w0k + accW[r]);
; #pragma unroll
;                     for (int r = 0; r < 4; ++r) cum = __builtin_amdgcn_mfma_f32_16x16x4f32((4 * lq + r <= l15) ? 1.0f : 0.0f, ld[r], cum, 0, 0, 0);
;                     float kmq[4], vq[4];
; #pragma unroll
;                     for (int r = 0; r < 4; ++r) { const int t = 4 * lq + r;
.LBB0_981:
	s_bitcmp1_b32 s31, 0
	s_cselect_b32 s26, 0x2400, 0
	s_add_i32 s68, s26, 0
	s_mul_i32 s26, s31, 0xaaab
	s_lshr_b32 s26, s26, 17
	s_mul_i32 s26, s26, 3
	s_sub_i32 s26, s31, s26
	s_mulk_i32 s26, 0x2940
	s_and_b32 s26, s26, 0xffc0
	s_waitcnt lgkmcnt(0)
	s_barrier
	s_add_i32 s33, s26, 0
	v_cndmask_b32_e64 v42, 0, 1, s[28:29]
	v_and_b32_e32 v75, 15, v73
	v_ashrrev_i32_e32 v74, 4, v73
	s_add_i32 s62, s33, 0xe380
	v_cmp_ne_u32_e64 s[26:27], 1, v42
	s_andn2_b64 vcc, exec, s[28:29]
	s_cbranch_vccnz .LBB0_993
	v_mul_u32_u24_e32 v42, 0xd0, v75
	v_lshlrev_b32_e32 v46, 4, v74
	v_add3_u32 v96, 0, v42, v46
	ds_read_b128 v[42:45], v96 offset:33152
	v_add_u32_e32 v100, v131, v46
	ds_read_b128 v[46:49], v100
	ds_read_b128 v[56:59], v96 offset:33216
	ds_read_b128 v[76:79], v100 offset:64
	s_waitcnt lgkmcnt(2)
	v_mfma_f32_16x16x32_bf16 v[42:45], v[42:45], v[46:49], 0
	ds_read_b128 v[46:49], v96 offset:33280
	ds_read_b128 v[80:83], v100 offset:128
	ds_read_b128 v[84:87], v96 offset:36480
	ds_read_b128 v[88:91], v100 offset:13312
	s_waitcnt lgkmcnt(4)
	v_mfma_f32_16x16x32_bf16 v[42:45], v[56:59], v[76:79], v[42:45]
	v_lshlrev_b32_e32 v58, 2, v74
	v_sub_u32_e32 v56, v75, v58
	v_cmp_gt_i32_e32 vcc, 0, v56
	s_waitcnt lgkmcnt(2)
	v_mfma_f32_16x16x32_bf16 v[42:45], v[46:49], v[80:83], v[42:45]
	v_cndmask_b32_e64 v46, 1.0, 0, vcc
	v_cmp_gt_i32_e32 vcc, 1, v56
	s_waitcnt lgkmcnt(0)
	v_mfma_f32_16x16x32_bf16 v[82:85], v[84:87], v[88:91], 0
	v_mov_b32_e32 v87, 0
	s_nop 0
	s_nop 1
	v_add_f32_e32 v42, v62, v42
	v_mul_f32_e32 v42, 0xbfb8aa3b, v42
	v_exp_f32_e32 v42, v42
	v_add_f32_e32 v43, v62, v43
	v_mul_f32_e32 v43, 0xbfb8aa3b, v43
	v_exp_f32_e32 v43, v43
	v_add_f32_e32 v42, 1.0, v42
	v_rcp_f32_e32 v42, v42
	v_add_f32_e32 v44, v62, v44
	v_add_f32_e32 v43, 1.0, v43
	v_rcp_f32_e32 v43, v43
	v_mul_f32_e32 v76, 0xbf1b4598, v42
	v_cndmask_b32_e64 v42, 1.0, 0, vcc
	v_mul_f32_e32 v44, 0xbfb8aa3b, v44
	v_mfma_f32_16x16x4_f32 v[46:49], v46, v76, 0
	v_exp_f32_e32 v44, v44
	v_mul_f32_e32 v57, 0xbf1b4598, v43
	v_cmp_gt_i32_e32 vcc, 2, v56
	v_add_f32_e32 v43, 1.0, v44
	v_rcp_f32_e32 v43, v43
	v_mfma_f32_16x16x4_f32 v[46:49], v42, v57, v[46:49]
	v_cndmask_b32_e64 v42, 1.0, 0, vcc
	v_mul_f32_e32 v77, 0xbf1b4598, v43
	v_cmp_gt_i32_e32 vcc, 3, v56
	s_nop 1
	v_cndmask_b32_e64 v56, 1.0, 0, vcc
	v_cmp_eq_u32_e32 vcc, 0, v75
	v_mfma_f32_16x16x4_f32 v[78:81], v42, v77, v[46:49]
	s_nop 1
	ds_read_b128 v[46:49], v96 offset:36544
	ds_read_b128 v[92:95], v100 offset:13376
	ds_read_b128 v[96:99], v96 offset:36608
	v_add_f32_e32 v42, v62, v45
	v_mul_f32_e32 v42, 0xbfb8aa3b, v42
	v_exp_f32_e32 v59, v42
	ds_read_b128 v[42:45], v100 offset:13440
	v_add_f32_e32 v59, 1.0, v59
	s_waitcnt lgkmcnt(2)
	v_mfma_f32_16x16x32_bf16 v[46:49], v[46:49], v[92:95], v[82:85]
	s_waitcnt lgkmcnt(0)
	v_mfma_f32_16x16x32_bf16 v[46:49], v[96:99], v[42:45], v[46:49]
	v_rcp_f32_e32 v42, v59
	s_nop 0
	v_mul_f32_e32 v59, 0xbf1b4598, v42
	s_nop 1
	v_mfma_f32_16x16x4_f32 v[42:45], v56, v59, v[78:81]
	v_lshl_or_b32 v56, v74, 8, v102
	v_lshl_add_u32 v78, v74, 9, v152
	v_lshl_add_u32 v79, v56, 1, 0
	s_nop 0
	v_add_f32_e32 v46, v63, v46
	ds_read_u16 v81, v78 offset:26752
	ds_read_u16 v79, v79 offset:26624
	ds_read_u16 v83, v78 offset:28928
	ds_read_u16 v80, v78 offset:31104
	ds_read_u16 v82, v78 offset:30976
	ds_read_u16 v78, v78 offset:28800
	v_mul_f32_e32 v46, 0xbfb8aa3b, v46
	v_exp_f32_e32 v46, v46
	s_waitcnt lgkmcnt(5)
	v_lshlrev_b32_e32 v81, 16, v81
	s_waitcnt lgkmcnt(4)
	v_lshlrev_b32_e32 v79, 16, v79
	s_waitcnt lgkmcnt(0)
	v_lshlrev_b32_e32 v84, 16, v78
	v_sub_f32_e32 v78, v79, v81
	v_add_f32_e32 v46, 1.0, v46
	v_fmac_f32_e32 v81, v3, v78
	v_rcp_f32_e32 v78, v46
	v_lshlrev_b32_e32 v83, 16, v83
	v_sub_f32_e32 v46, v84, v83
	v_fmac_f32_e32 v83, v60, v46
	v_add_f32_e32 v46, -1.0, v78
	s_nop 0
	v_fma_f32 v46, v65, v46, 1.0
	v_mul_f32_e32 v79, v64, v83
	v_mul_f32_e32 v83, v46, v83
	v_mul_f32_e32 v85, v81, v83
	v_mul_f32_e32 v46, v79, v79
	v_mov_b32_e32 v84, 0
	s_nop 0
	v_mul_f32_e32 v86, v66, v85
	v_mov_b32_dpp v84, v46 quad_perm:[1,0,3,2] row_mask:0xf bank_mask:0xf
	s_nop 0
	v_mov_b32_dpp v87, v86 quad_perm:[1,0,3,2] row_mask:0xf bank_mask:0xf
	v_fmac_f32_e32 v84, v79, v79
	v_fmac_f32_e32 v87, v66, v85
	v_mov_b32_e32 v86, 0
	v_add_f32_dpp v46, v84, v84 quad_perm:[2,3,0,1] row_mask:0xf bank_mask:0xf bound_ctrl:1
	v_add_f32_dpp v85, v87, v87 quad_perm:[2,3,0,1] row_mask:0xf bank_mask:0xf bound_ctrl:1
	v_mov_b32_e32 v84, 0
	v_add_f32_dpp v46, v46, v46 row_half_mirror row_mask:0xf bank_mask:0xf bound_ctrl:1
	v_add_f32_dpp v85, v85, v85 row_half_mirror row_mask:0xf bank_mask:0xf bound_ctrl:1
	s_nop 0
	v_mov_b32_dpp v84, v46 row_mirror row_mask:0xf bank_mask:0xf
	v_mov_b32_dpp v86, v85 row_mirror row_mask:0xf bank_mask:0xf
	s_and_saveexec_b64 s[28:29], vcc
	s_cbranch_execz .LBB0_984
	v_add_f32_e32 v46, v46, v84
	v_add_f32_e32 v84, v85, v86
	v_or_b32_e32 v85, s88, v73
	v_lshl_add_u32 v85, v85, 2, 0
	v_add_u32_e32 v86, 0x19b40, v85
	v_add_u32_e32 v85, 0x19c40, v85
	ds_write_b32 v86, v46
	ds_write_b32 v85, v84
